# P0 row loop software-pipelined by one row: next row's loads in flight while the current row is normalised
# speedup vs baseline: 1.0057x; 1.0057x over previous
; #define LAS __attribute__((address_space(3)))
; template <int MODE  > ...
;     ...
;     for (int row = gwave; row < T; row += nwaves) {
;         const float4* xr = (const float4*)(in + (size_t)row * D) + lane; const uint2* xb = (const uint2*)((const bf16*)in + (size_t)row * D) + lane;
;         float4 v[4]; float ss = 0.f;
; #pragma unroll
;         for (int j = 0; j < 4; ++j) {
;             if (MODE == 2) { const uint2 w = xb[64 * j]; v[j] = make_float4(__uint_as_float(w.x << 16), __uint_as_float(w.x & 0xffff0000u), __uint_as_float(w.y << 16), __uint_as_float(w.y & 0xffff0000u)); }
;             else if (MODE == 1) { typedef float f4v __attribute__((ext_vector_type(4))); const f4v t4 = __builtin_nontemporal_load((const f4v*)xr + 64 * j); v[j] = make_float4(t4.x, t4.y, t4.z, t4.w); }
;             else v[j] = xr[64 * j];
;             ss += v[j].x * v[j].x + v[j].y * v[j].y + v[j].z * v[j].z + v[j].w * v[j].w; }
;         ss = wave_sum(ss);
;         const float r = rsqrtf(ss * (1.f / D) + EPS);
;         unsigned long long* o8 = (unsigned long long*)(outp + (size_t)row * D) + lane;
;         float dacc[8]; float y[4][4]; float mx = 0.f;
; #pragma unroll
;         for (int h = 0; h < 8; ++h) dacc[h] = 0.f;
; #pragma unroll
;         for (int j = 0; j < 4; ++j) {
;             const float4 gv = ((const float4*)g)[lane + 64 * j];
;             y[j][0] = v[j].x * r * gv.x; y[j][1] = v[j].y * r * gv.y; y[j][2] = v[j].z * r * gv.z; y[j][3] = v[j].w * r * gv.w;
;             o8[64 * j] = (unsigned long long)pk2(y[j][0], y[j][1]) | ((unsigned long long)pk2(y[j][2], y[j][3]) << 32);
;             if (MODE == 2) mx = fmaxf(mx, fmaxf(fmaxf(fabsf(y[j][0]), fabsf(y[j][1])), fmaxf(fabsf(y[j][2]), fabsf(y[j][3]))));
;             if (MODE == 1) {
; #pragma unroll
;                 for (int h = 0; h < 8; ++h) {
;                     typedef float f4v __attribute__((ext_vector_type(4)));
;                     const f4v wv = *(const LAS f4v*)(ldsb + h * 16384 + 8448 + (256 * j + 4 * lane) * 4);
.LBB0_26:
	s_or_b64 exec, exec, s[0:1]
	s_movk_i32 s0, 0x4000
	v_cmp_gt_i32_e32 vcc, s0, v154
	s_waitcnt lgkmcnt(0)
	s_barrier
	s_and_saveexec_b64 s[10:11], vcc
	s_cbranch_execz .LBB0_31
	v_readlane_b32 s36, v235, 0
	v_lshlrev_b32_e32 v1, 4, v42
	v_readlane_b32 s38, v235, 2
	v_readlane_b32 s39, v235, 3
	s_nop 4
	global_load_dwordx4 v[2:5], v1, s[38:39]
	global_load_dwordx4 v[6:9], v1, s[38:39] offset:1024
	global_load_dwordx4 v[10:13], v1, s[38:39] offset:2048
	global_load_dwordx4 v[14:17], v1, s[38:39] offset:3072
	v_ashrrev_i32_e32 v155, 31, v154
	v_lshlrev_b64 v[158:159], 11, v[154:155]
	v_cmp_eq_u32_e64 s[4:5], 0, v42
	v_lshl_or_b32 v158, v42, 3, v158
	v_lshlrev_b64 v[42:43], 12, v[154:155]
	v_readlane_b32 s37, v235, 1
	v_add_u32_e32 v126, 0, v1
	v_or_b32_e32 v42, v42, v1
	v_add_u32_e32 v18, 0x12100, v126
	v_add_u32_e32 v22, 0x16100, v126
	v_add_u32_e32 v26, 0x1a100, v126
	v_add_u32_e32 v30, 0x1e100, v126
	v_add_u32_e32 v34, 0x12500, v126
	v_add_u32_e32 v38, 0x16500, v126
	v_add_u32_e32 v46, 0x1a500, v126
	v_add_u32_e32 v47, 0x1e500, v126
	v_add_u32_e32 v50, 0x12900, v126
	v_add_u32_e32 v54, 0x16900, v126
	v_add_u32_e32 v58, 0x1a900, v126
	v_add_u32_e32 v62, 0x1e900, v126
	v_add_u32_e32 v130, 0x12d00, v126
	v_add_u32_e32 v134, 0x16d00, v126
	v_add_u32_e32 v138, 0x1ad00, v126
	v_add_u32_e32 v142, 0x1ed00, v126
	v_mov_b64_e32 v[44:45], 0x9390000
	v_lshl_add_u64 v[42:43], s[36:37], 0, v[42:43]
	s_mov_b64 s[0:1], 0xc00
	ds_read_b128 v[18:21], v18
	ds_read_b128 v[22:25], v22
	ds_read_b128 v[26:29], v26
	ds_read_b128 v[30:33], v30
	ds_read_b128 v[34:37], v34
	ds_read_b128 v[38:41], v38
	v_lshl_add_u64 v[156:157], v[154:155], 2, v[44:45]
	v_lshl_add_u64 v[160:161], v[42:43], 0, s[0:1]
	ds_read_b128 v[42:45], v46
	ds_read_b128 v[46:49], v47
	ds_read_b128 v[50:53], v50
	ds_read_b128 v[54:57], v54
	ds_read_b128 v[58:61], v58
	ds_read_b128 v[62:65], v62
	ds_read_b128 v[66:69], v126 offset:8448
	ds_read_b128 v[70:73], v126 offset:9472
	ds_read_b128 v[74:77], v126 offset:24832
	ds_read_b128 v[78:81], v126 offset:25856
	ds_read_b128 v[82:85], v126 offset:41216
	ds_read_b128 v[86:89], v126 offset:42240
	ds_read_b128 v[90:93], v126 offset:57600
	ds_read_b128 v[94:97], v126 offset:58624
	ds_read_b128 v[98:101], v126 offset:10496
	ds_read_b128 v[102:105], v126 offset:11520
	ds_read_b128 v[106:109], v126 offset:26880
	ds_read_b128 v[110:113], v126 offset:27904
	ds_read_b128 v[114:117], v126 offset:43264
	ds_read_b128 v[118:121], v126 offset:44288
	ds_read_b128 v[122:125], v126 offset:59648
	ds_read_b128 v[126:129], v126 offset:60672
	ds_read_b128 v[130:133], v130
	ds_read_b128 v[134:137], v134
	ds_read_b128 v[138:141], v138
	ds_read_b128 v[142:145], v142
	v_readlane_b32 s40, v235, 4
	s_ashr_i32 s9, s8, 31
	s_lshl_b64 s[12:13], s[8:9], 2
	s_lshl_b64 s[14:15], s[8:9], 5
	s_lshl_b64 s[16:17], s[8:9], 11
	s_lshl_b64 s[18:19], s[8:9], 12
	s_mov_b64 s[20:21], 0
	v_mov_b32_e32 v1, 0x358637bd
	s_mov_b32 s3, 0x5200000
	s_mov_b32 s9, 0x9200000
	s_movk_i32 s40, 0x3fff
	v_lshlrev_b64 v[162:163], 5, v[154:155]
	v_readlane_b32 s41, v235, 5
	v_readlane_b32 s42, v235, 6
	v_readlane_b32 s43, v235, 7
	v_readlane_b32 s44, v235, 8
	v_readlane_b32 s45, v235, 9
	v_readlane_b32 s46, v235, 10
	v_readlane_b32 s47, v235, 11
	v_readlane_b32 s48, v235, 12
	v_readlane_b32 s49, v235, 13
	v_readlane_b32 s50, v235, 14
	v_readlane_b32 s51, v235, 15
	global_load_dwordx4 v[236:239], v[160:161], off offset:-3072 nt
	global_load_dwordx4 v[240:243], v[160:161], off offset:-2048 nt
	global_load_dwordx4 v[244:247], v[160:161], off offset:-1024 nt
	global_load_dwordx4 v[248:251], v[160:161], off nt
	s_waitcnt vmcnt(0)
	s_branch .LBB0_29

; #define LAS __attribute__((address_space(3)))
; template <int MODE  > ...
;     ...
;         const float4* xr = (const float4*)(in + (size_t)row * D) + lane; const uint2* xb = (const uint2*)((const bf16*)in + (size_t)row * D) + lane;
;         float4 v[4]; float ss = 0.f;
; #pragma unroll
;         for (int j = 0; j < 4; ++j) {
;             if (MODE == 2) { const uint2 w = xb[64 * j]; v[j] = make_float4(__uint_as_float(w.x << 16), __uint_as_float(w.x & 0xffff0000u), __uint_as_float(w.y << 16), __uint_as_float(w.y & 0xffff0000u)); }
;             else if (MODE == 1) { typedef float f4v __attribute__((ext_vector_type(4))); const f4v t4 = __builtin_nontemporal_load((const f4v*)xr + 64 * j); v[j] = make_float4(t4.x, t4.y, t4.z, t4.w); }
;             else v[j] = xr[64 * j];
;             ss += v[j].x * v[j].x + v[j].y * v[j].y + v[j].z * v[j].z + v[j].w * v[j].w; }
;         ss = wave_sum(ss);
;         const float r = rsqrtf(ss * (1.f / D) + EPS);
;         unsigned long long* o8 = (unsigned long long*)(outp + (size_t)row * D) + lane;
;         float dacc[8]; float y[4][4]; float mx = 0.f;
; #pragma unroll
;         for (int h = 0; h < 8; ++h) dacc[h] = 0.f;
; #pragma unroll
;         for (int j = 0; j < 4; ++j) {
;             const float4 gv = ((const float4*)g)[lane + 64 * j];
;             y[j][0] = v[j].x * r * gv.x; y[j][1] = v[j].y * r * gv.y; y[j][2] = v[j].z * r * gv.z; y[j][3] = v[j].w * r * gv.w;
;             o8[64 * j] = (unsigned long long)pk2(y[j][0], y[j][1]) | ((unsigned long long)pk2(y[j][2], y[j][3]) << 32);
;             if (MODE == 2) mx = fmaxf(mx, fmaxf(fmaxf(fabsf(y[j][0]), fabsf(y[j][1])), fmaxf(fabsf(y[j][2]), fabsf(y[j][3]))));
;             if (MODE == 1) {
; #pragma unroll
;                 for (int h = 0; h < 8; ++h) {
;                     typedef float f4v __attribute__((ext_vector_type(4)));
;                     const f4v wv = *(const LAS f4v*)(ldsb + h * 16384 + 8448 + (256 * j + 4 * lane) * 4);
;                     dacc[h] += y[j][0] * wv.x + y[j][1] * wv.y + y[j][2] * wv.z + y[j][3] * wv.w;
.LBB0_29:
	s_waitcnt vmcnt(7)
	v_mov_b32_e32 v168, v236
	v_mov_b32_e32 v169, v237
	v_mov_b32_e32 v170, v238
	v_mov_b32_e32 v171, v239
	v_mov_b32_e32 v150, v240
	v_mov_b32_e32 v151, v241
	v_mov_b32_e32 v152, v242
	v_mov_b32_e32 v153, v243
	v_mov_b32_e32 v172, v244
	v_mov_b32_e32 v173, v245
	v_mov_b32_e32 v174, v246
	v_mov_b32_e32 v175, v247
	v_mov_b32_e32 v146, v248
	v_mov_b32_e32 v147, v249
	v_mov_b32_e32 v148, v250
	v_mov_b32_e32 v149, v251
	v_add_u32_e32 v252, s8, v154
	v_cmp_lt_i32_e32 vcc, s40, v252
	v_lshl_add_u64 v[252:253], v[160:161], 0, s[18:19]
	s_nop 1
	v_cndmask_b32_e32 v252, v252, v160, vcc
	v_cndmask_b32_e32 v253, v253, v161, vcc
	global_load_dwordx4 v[236:239], v[252:253], off offset:-3072 nt
	global_load_dwordx4 v[240:243], v[252:253], off offset:-2048 nt
	global_load_dwordx4 v[244:247], v[252:253], off offset:-1024 nt
	global_load_dwordx4 v[248:251], v[252:253], off nt
	s_mov_b32 s22, 0x800000
	v_lshl_add_u64 v[164:165], s[90:91], 0, v[158:159]
	s_nop 0
	v_mov_b32_e32 v176, v169
	s_nop 0
	v_mov_b32_e32 v177, v151
	v_mov_b32_e32 v166, v168
	v_mov_b32_e32 v167, v150
	s_nop 0
	v_mov_b32_e32 v180, v173
	s_nop 0
	v_mov_b32_e32 v181, v147
	v_pk_mul_f32 v[176:177], v[176:177], v[176:177]
	v_mov_b32_e32 v178, v172
	v_mov_b32_e32 v179, v146
	v_mov_b32_e32 v182, v170
	v_mov_b32_e32 v183, v152
	v_pk_mul_f32 v[180:181], v[180:181], v[180:181]
	v_pk_fma_f32 v[166:167], v[166:167], v[166:167], v[176:177]
	v_mov_b32_e32 v184, v174
	v_mov_b32_e32 v185, v148
	v_mov_b32_e32 v186, v171
	v_mov_b32_e32 v187, v153
	v_pk_fma_f32 v[176:177], v[178:179], v[178:179], v[180:181]
	v_pk_fma_f32 v[166:167], v[182:183], v[182:183], v[166:167]
	v_mov_b32_e32 v188, v175
	v_mov_b32_e32 v189, v149
	v_pk_fma_f32 v[176:177], v[184:185], v[184:185], v[176:177]
	v_pk_fma_f32 v[166:167], v[186:187], v[186:187], v[166:167]
	v_pk_fma_f32 v[176:177], v[188:189], v[188:189], v[176:177]
	v_add_f32_e32 v155, v166, v167
	v_add_f32_e32 v155, v155, v176
	v_add_f32_e32 v155, v155, v177
	s_nop 1
	v_add_f32_dpp v155, v155, v155 quad_perm:[1,0,3,2] row_mask:0xf bank_mask:0xf bound_ctrl:1
	s_nop 1
	v_add_f32_dpp v155, v155, v155 quad_perm:[2,3,0,1] row_mask:0xf bank_mask:0xf bound_ctrl:1
	s_nop 1
	v_add_f32_dpp v155, v155, v155 row_half_mirror row_mask:0xf bank_mask:0xf bound_ctrl:1
	s_nop 1
	v_add_f32_dpp v155, v155, v155 row_mirror row_mask:0xf bank_mask:0xf bound_ctrl:1
	s_nop 0
	v_readlane_b32 s23, v155, 16
	v_readlane_b32 s24, v155, 48
	v_readlane_b32 s0, v155, 0
	v_readlane_b32 s1, v155, 32
	v_mov_b32_e32 v166, s23
	v_mov_b32_e32 v167, s24
	v_pk_add_f32 v[166:167], s[0:1], v[166:167]
	s_nop 0
	v_add_f32_e32 v155, v166, v167
	v_fmamk_f32 v155, v155, 0x3a800000, v1
	v_mul_f32_e32 v166, 0x4b800000, v155
	v_cmp_gt_f32_e32 vcc, s22, v155
	s_nop 1
	v_cndmask_b32_e32 v155, v155, v166, vcc
	v_rsq_f32_e32 v155, v155
	v_add_co_u32_e64 v166, s[0:1], s3, v164
	v_mul_f32_e32 v164, 0x45800000, v155
	v_cndmask_b32_e32 v164, v155, v164, vcc
	v_pk_mul_f32 v[168:169], v[168:169], v[164:165] op_sel_hi:[1,0]
	v_pk_mul_f32 v[170:171], v[170:171], v[164:165] op_sel_hi:[1,0]
	v_pk_mul_f32 v[146:147], v[146:147], v[164:165] op_sel_hi:[1,0]
	v_pk_mul_f32 v[148:149], v[148:149], v[164:165] op_sel_hi:[1,0]
	v_pk_mul_f32 v[168:169], v[2:3], v[168:169]
	v_addc_co_u32_e64 v167, s[0:1], 0, v165, s[0:1]
	v_pk_mul_f32 v[150:151], v[150:151], v[164:165] op_sel_hi:[1,0]
	v_pk_mul_f32 v[152:153], v[152:153], v[164:165] op_sel_hi:[1,0]
	v_pk_mul_f32 v[172:173], v[172:173], v[164:165] op_sel_hi:[1,0]
	v_pk_mul_f32 v[174:175], v[174:175], v[164:165] op_sel_hi:[1,0]
	v_pk_mul_f32 v[170:171], v[4:5], v[170:171]
	v_pk_mul_f32 v[176:177], v[14:15], v[146:147]
	v_pk_mul_f32 v[146:147], v[16:17], v[148:149]
	v_cvt_pk_bf16_f32 v148, v168, v169
	s_waitcnt lgkmcnt(14)
	v_mul_f32_e32 v155, v67, v169
	v_mul_f32_e32 v165, v75, v169
	v_mul_f32_e32 v184, v83, v169
	s_waitcnt lgkmcnt(13)
	v_mul_f32_e32 v185, v91, v169
	v_mul_f32_e32 v186, v19, v169
	v_mul_f32_e32 v187, v23, v169
	v_mul_f32_e32 v188, v27, v169
	v_mul_f32_e32 v169, v31, v169
	v_pk_mul_f32 v[150:151], v[6:7], v[150:151]
	v_pk_mul_f32 v[152:153], v[8:9], v[152:153]
	v_pk_mul_f32 v[172:173], v[10:11], v[172:173]
	v_pk_mul_f32 v[174:175], v[12:13], v[174:175]
	v_cvt_pk_bf16_f32 v149, v170, v171
	v_fmac_f32_e32 v155, v66, v168
	v_fmac_f32_e32 v165, v74, v168
	v_fmac_f32_e32 v184, v82, v168
	v_fmac_f32_e32 v185, v90, v168
	v_fmac_f32_e32 v186, v18, v168
	v_fmac_f32_e32 v187, v22, v168
	v_fmac_f32_e32 v188, v26, v168
	v_fmac_f32_e32 v169, v30, v168
	v_cvt_pk_bf16_f32 v178, v150, v151
	v_cvt_pk_bf16_f32 v179, v152, v153
	v_cvt_pk_bf16_f32 v180, v172, v173
	v_cvt_pk_bf16_f32 v181, v174, v175
	v_cvt_pk_bf16_f32 v182, v176, v177
	v_cvt_pk_bf16_f32 v183, v146, v147
	global_store_dwordx2 v[166:167], v[148:149], off
	global_store_dwordx2 v[166:167], v[178:179], off offset:512
	global_store_dwordx2 v[166:167], v[180:181], off offset:1024
	global_store_dwordx2 v[166:167], v[182:183], off offset:1536
	v_fmac_f32_e32 v155, v68, v170
	v_fmac_f32_e32 v165, v76, v170
	v_fmac_f32_e32 v184, v84, v170
	v_fmac_f32_e32 v185, v92, v170
	v_fmac_f32_e32 v186, v20, v170
	v_fmac_f32_e32 v187, v24, v170
	v_fmac_f32_e32 v188, v28, v170
	v_fmac_f32_e32 v169, v32, v170
	v_mul_f32_e32 v148, v71, v151
	v_fmac_f32_e32 v155, v69, v171
	v_fmac_f32_e32 v165, v77, v171
	v_fmac_f32_e32 v184, v85, v171
	v_fmac_f32_e32 v185, v93, v171
	v_fmac_f32_e32 v186, v21, v171
	v_fmac_f32_e32 v187, v25, v171
	v_fmac_f32_e32 v188, v29, v171
	v_fmac_f32_e32 v169, v33, v171
	v_fmac_f32_e32 v148, v70, v150
	v_mul_f32_e32 v149, v79, v151
	v_mul_f32_e32 v166, v87, v151
	s_waitcnt lgkmcnt(12)
; #define LAS __attribute__((address_space(3)))
; template <int MODE  > ...
;     ...
;                 for (int h = 0; h < 8; ++h) {
;                     typedef float f4v __attribute__((ext_vector_type(4)));
;                     const f4v wv = *(const LAS f4v*)(ldsb + h * 16384 + 8448 + (256 * j + 4 * lane) * 4);
;                     dacc[h] += y[j][0] * wv.x + y[j][1] * wv.y + y[j][2] * wv.z + y[j][3] * wv.w;
	v_mul_f32_e32 v167, v95, v151
	v_mul_f32_e32 v168, v35, v151
	v_mul_f32_e32 v170, v39, v151
	v_mul_f32_e32 v171, v43, v151
	v_mul_f32_e32 v151, v47, v151
	v_fmac_f32_e32 v149, v78, v150
	v_fmac_f32_e32 v166, v86, v150
	v_fmac_f32_e32 v167, v94, v150
	v_fmac_f32_e32 v168, v34, v150
	v_fmac_f32_e32 v170, v38, v150
	v_fmac_f32_e32 v171, v42, v150
	v_fmac_f32_e32 v151, v46, v150
	v_fmac_f32_e32 v148, v72, v152
	v_fmac_f32_e32 v148, v73, v153
	v_fmac_f32_e32 v149, v80, v152
	v_fmac_f32_e32 v166, v88, v152
	v_fmac_f32_e32 v167, v96, v152
	v_fmac_f32_e32 v168, v36, v152
	v_fmac_f32_e32 v170, v40, v152
	v_fmac_f32_e32 v171, v44, v152
	v_fmac_f32_e32 v151, v48, v152
	v_add_f32_e32 v155, 0, v155
	v_fmac_f32_e32 v149, v81, v153
	v_fmac_f32_e32 v166, v89, v153
	v_fmac_f32_e32 v167, v97, v153
	v_fmac_f32_e32 v168, v37, v153
	v_fmac_f32_e32 v170, v41, v153
	v_fmac_f32_e32 v171, v45, v153
	v_fmac_f32_e32 v151, v49, v153
	s_waitcnt lgkmcnt(11)
	v_mul_f32_e32 v150, v99, v173
	s_waitcnt lgkmcnt(7)
	v_mul_f32_e32 v153, v115, v173
	v_mul_f32_e32 v179, v51, v173
	v_add_f32_e32 v148, v148, v155
	v_add_f32_e32 v155, 0, v165
	v_fmac_f32_e32 v150, v98, v172
	v_fmac_f32_e32 v153, v114, v172
	v_fmac_f32_e32 v179, v50, v172
	v_add_f32_e32 v149, v149, v155
	v_add_f32_e32 v155, 0, v184
	v_fmac_f32_e32 v150, v100, v174
	v_fmac_f32_e32 v153, v116, v174
	v_fmac_f32_e32 v179, v52, v174
	v_add_f32_e32 v155, v166, v155
	v_add_f32_e32 v166, 0, v186
	v_fmac_f32_e32 v150, v101, v175
	v_fmac_f32_e32 v153, v117, v175
	v_fmac_f32_e32 v179, v53, v175
	v_add_f32_e32 v166, v168, v166
	v_add_f32_e32 v148, v150, v148
	v_add_f32_e32 v150, v153, v155
	v_add_f32_e32 v153, v179, v166
	v_mul_f32_e32 v166, v103, v177
	v_fmac_f32_e32 v166, v102, v176
	v_fmac_f32_e32 v166, v104, v146
	v_mul_f32_e32 v152, v107, v173
	v_fmac_f32_e32 v166, v105, v147
	v_fmac_f32_e32 v152, v106, v172
	v_add_f32_e32 v148, v166, v148
	v_mul_f32_e32 v166, v111, v177
	v_fmac_f32_e32 v152, v108, v174
	v_fmac_f32_e32 v166, v110, v176
	v_fmac_f32_e32 v152, v109, v175
	v_fmac_f32_e32 v166, v112, v146
	v_add_f32_e32 v149, v152, v149
	v_fmac_f32_e32 v166, v113, v147
	v_add_f32_e32 v149, v166, v149
	s_waitcnt lgkmcnt(6)
	v_mul_f32_e32 v166, v119, v177
	v_fmac_f32_e32 v166, v118, v176
	v_fmac_f32_e32 v166, v120, v146
	s_waitcnt lgkmcnt(5)
	v_mul_f32_e32 v178, v123, v173
	v_fmac_f32_e32 v166, v121, v147
	v_fmac_f32_e32 v178, v122, v172
	v_add_f32_e32 v150, v166, v150
	s_waitcnt lgkmcnt(4)
	v_mul_f32_e32 v166, v127, v177
	v_fmac_f32_e32 v178, v124, v174
	v_add_f32_e32 v165, 0, v185
	v_fmac_f32_e32 v166, v126, v176
	v_fmac_f32_e32 v178, v125, v175
	v_add_f32_e32 v165, v167, v165
	v_fmac_f32_e32 v166, v128, v146
	v_add_f32_e32 v152, v178, v165
	v_fmac_f32_e32 v166, v129, v147
	v_add_f32_e32 v152, v166, v152
	s_waitcnt lgkmcnt(3)
	v_mul_f32_e32 v166, v131, v177
	v_fmac_f32_e32 v166, v130, v176
	v_fmac_f32_e32 v166, v132, v146
	v_mul_f32_e32 v180, v55, v173
	v_fmac_f32_e32 v166, v133, v147
	v_fmac_f32_e32 v180, v54, v172
	v_add_f32_e32 v153, v166, v153
	s_waitcnt lgkmcnt(2)
	v_mul_f32_e32 v166, v135, v177
	v_fmac_f32_e32 v180, v56, v174
	v_add_f32_e32 v167, 0, v187
	v_fmac_f32_e32 v166, v134, v176
	v_fmac_f32_e32 v180, v57, v175
	v_add_f32_e32 v167, v170, v167
	v_fmac_f32_e32 v166, v136, v146
	v_mul_f32_e32 v181, v59, v173
	v_add_f32_e32 v155, v180, v167
	v_fmac_f32_e32 v166, v137, v147
	v_fmac_f32_e32 v181, v58, v172
	v_add_f32_e32 v155, v166, v155
	s_waitcnt lgkmcnt(1)
	v_mul_f32_e32 v166, v139, v177
	v_fmac_f32_e32 v181, v60, v174
	v_add_f32_e32 v168, 0, v188
	v_fmac_f32_e32 v166, v138, v176
	v_fmac_f32_e32 v181, v61, v175
	v_add_f32_e32 v168, v171, v168
	v_fmac_f32_e32 v166, v140, v146
	v_add_f32_e32 v165, v181, v168
	v_fmac_f32_e32 v166, v141, v147
	v_add_f32_e32 v165, v166, v165
	s_waitcnt lgkmcnt(0)
; template <int MODE  > ...
;     ...
;         if (MODE == 1) {
; #pragma unroll
;             for (int h = 0; h < 8; ++h) dacc[h] = wave_sum(dacc[h]);
;             if (lane == 0) { float4* dp = (float4*)(dtraw + (size_t)row * 8); dp[0] = make_float4(dacc[0], dacc[1], dacc[2], dacc[3]); dp[1] = make_float4(dacc[4], dacc[5], dacc[6], dacc[7]); xs[row] = 1.f / r; }
;         }
	v_mul_f32_e32 v166, v143, v177
	v_fmac_f32_e32 v166, v142, v176
	v_fmac_f32_e32 v166, v144, v146
	v_fmac_f32_e32 v166, v145, v147
	v_add_f32_dpp v147, v148, v148 quad_perm:[1,0,3,2] row_mask:0xf bank_mask:0xf bound_ctrl:1
	v_mul_f32_e32 v173, v63, v173
	v_fmac_f32_e32 v173, v62, v172
	v_add_f32_dpp v147, v147, v147 quad_perm:[2,3,0,1] row_mask:0xf bank_mask:0xf bound_ctrl:1
	v_fmac_f32_e32 v173, v64, v174
	v_add_f32_e32 v169, 0, v169
	v_add_f32_dpp v147, v147, v147 row_half_mirror row_mask:0xf bank_mask:0xf bound_ctrl:1
	v_fmac_f32_e32 v173, v65, v175
	v_add_f32_e32 v151, v151, v169
	v_add_f32_dpp v147, v147, v147 row_mirror row_mask:0xf bank_mask:0xf bound_ctrl:1
	v_add_f32_e32 v151, v173, v151
	v_readlane_b32 s0, v147, 0
	v_readlane_b32 s42, v147, 16
	v_readlane_b32 s22, v147, 32
	v_readlane_b32 s41, v147, 48
	v_add_f32_dpp v147, v149, v149 quad_perm:[1,0,3,2] row_mask:0xf bank_mask:0xf bound_ctrl:1
	v_add_f32_e32 v146, v166, v151
	s_nop 0
	v_add_f32_dpp v147, v147, v147 quad_perm:[2,3,0,1] row_mask:0xf bank_mask:0xf bound_ctrl:1
	v_add_f32_dpp v146, v146, v146 quad_perm:[1,0,3,2] row_mask:0xf bank_mask:0xf bound_ctrl:1
	s_nop 0
	v_add_f32_dpp v147, v147, v147 row_half_mirror row_mask:0xf bank_mask:0xf bound_ctrl:1
	v_add_f32_dpp v146, v146, v146 quad_perm:[2,3,0,1] row_mask:0xf bank_mask:0xf bound_ctrl:1
	s_nop 0
	v_add_f32_dpp v147, v147, v147 row_mirror row_mask:0xf bank_mask:0xf bound_ctrl:1
	v_add_f32_dpp v146, v146, v146 row_half_mirror row_mask:0xf bank_mask:0xf bound_ctrl:1
	v_readlane_b32 s1, v147, 0
	v_readlane_b32 s44, v147, 16
	v_readlane_b32 s23, v147, 32
	v_readlane_b32 s43, v147, 48
	v_add_f32_dpp v147, v150, v150 quad_perm:[1,0,3,2] row_mask:0xf bank_mask:0xf bound_ctrl:1
	v_add_f32_dpp v146, v146, v146 row_mirror row_mask:0xf bank_mask:0xf bound_ctrl:1
	s_nop 0
	v_add_f32_dpp v147, v147, v147 quad_perm:[2,3,0,1] row_mask:0xf bank_mask:0xf bound_ctrl:1
	v_readlane_b32 s39, v146, 0
	v_readlane_b32 s70, v146, 16
	v_add_f32_dpp v147, v147, v147 row_half_mirror row_mask:0xf bank_mask:0xf bound_ctrl:1
	v_readlane_b32 s37, v146, 32
	v_readlane_b32 s69, v146, 48
	v_add_f32_dpp v147, v147, v147 row_mirror row_mask:0xf bank_mask:0xf bound_ctrl:1
	s_nop 0
	v_readlane_b32 s24, v147, 0
	v_readlane_b32 s46, v147, 16
	v_readlane_b32 s28, v147, 32
	v_readlane_b32 s45, v147, 48
	v_add_f32_dpp v147, v152, v152 quad_perm:[1,0,3,2] row_mask:0xf bank_mask:0xf bound_ctrl:1
	s_nop 1
	v_add_f32_dpp v147, v147, v147 quad_perm:[2,3,0,1] row_mask:0xf bank_mask:0xf bound_ctrl:1
	s_nop 1
	v_add_f32_dpp v147, v147, v147 row_half_mirror row_mask:0xf bank_mask:0xf bound_ctrl:1
	s_nop 1
	v_add_f32_dpp v147, v147, v147 row_mirror row_mask:0xf bank_mask:0xf bound_ctrl:1
	s_nop 0
	v_readlane_b32 s25, v147, 0
	v_readlane_b32 s48, v147, 16
	v_readlane_b32 s29, v147, 32
	v_readlane_b32 s47, v147, 48
	v_add_f32_dpp v147, v153, v153 quad_perm:[1,0,3,2] row_mask:0xf bank_mask:0xf bound_ctrl:1
	s_nop 1
	v_add_f32_dpp v147, v147, v147 quad_perm:[2,3,0,1] row_mask:0xf bank_mask:0xf bound_ctrl:1
	s_nop 1
	v_add_f32_dpp v147, v147, v147 row_half_mirror row_mask:0xf bank_mask:0xf bound_ctrl:1
	s_nop 1
	v_add_f32_dpp v147, v147, v147 row_mirror row_mask:0xf bank_mask:0xf bound_ctrl:1
	s_nop 0
	v_readlane_b32 s30, v147, 0
	v_readlane_b32 s50, v147, 16
	v_readlane_b32 s34, v147, 32
	v_readlane_b32 s49, v147, 48
	v_add_f32_dpp v147, v155, v155 quad_perm:[1,0,3,2] row_mask:0xf bank_mask:0xf bound_ctrl:1
	s_nop 1
	v_add_f32_dpp v147, v147, v147 quad_perm:[2,3,0,1] row_mask:0xf bank_mask:0xf bound_ctrl:1
	s_nop 1
	v_add_f32_dpp v147, v147, v147 row_half_mirror row_mask:0xf bank_mask:0xf bound_ctrl:1
	s_nop 1
	v_add_f32_dpp v147, v147, v147 row_mirror row_mask:0xf bank_mask:0xf bound_ctrl:1
	s_nop 0
	v_readlane_b32 s31, v147, 0
	v_readlane_b32 s64, v147, 16
	v_readlane_b32 s35, v147, 32
	v_readlane_b32 s51, v147, 48
	v_add_f32_dpp v147, v165, v165 quad_perm:[1,0,3,2] row_mask:0xf bank_mask:0xf bound_ctrl:1
	s_nop 1
	v_add_f32_dpp v147, v147, v147 quad_perm:[2,3,0,1] row_mask:0xf bank_mask:0xf bound_ctrl:1
	s_nop 1
	v_add_f32_dpp v147, v147, v147 row_half_mirror row_mask:0xf bank_mask:0xf bound_ctrl:1
	s_nop 1
	v_add_f32_dpp v147, v147, v147 row_mirror row_mask:0xf bank_mask:0xf bound_ctrl:1
	s_nop 0
	v_readlane_b32 s38, v147, 0
	v_readlane_b32 s68, v147, 16
	v_readlane_b32 s36, v147, 32
	v_readlane_b32 s65, v147, 48
	s_and_saveexec_b64 s[26:27], s[4:5]
	s_cbranch_execz .LBB0_28
	v_mov_b32_e32 v148, s46
	v_mov_b32_e32 v149, s48
	v_mov_b32_e32 v170, s45
	v_mov_b32_e32 v171, s47
	v_mov_b32_e32 v146, s42
	v_mov_b32_e32 v147, s44
	v_mov_b32_e32 v172, s41
	v_mov_b32_e32 v173, s43
	v_lshl_add_u64 v[174:175], s[90:91], 0, v[162:163]
	v_pk_add_f32 v[148:149], s[24:25], v[148:149]
	v_pk_add_f32 v[170:171], s[28:29], v[170:171]
	v_pk_add_f32 v[146:147], s[0:1], v[146:147]
	v_pk_add_f32 v[172:173], s[22:23], v[172:173]
	v_pk_add_f32 v[148:149], v[148:149], v[170:171]
	v_add_co_u32_e32 v170, vcc, s9, v174
	v_div_scale_f32 v155, s[0:1], v164, v164, 1.0
	v_mov_b32_e32 v166, s50
	v_mov_b32_e32 v167, s64
	v_mov_b32_e32 v168, s49
	v_mov_b32_e32 v169, s51
	v_pk_add_f32 v[146:147], v[146:147], v[172:173]
	v_addc_co_u32_e32 v171, vcc, 0, v175, vcc
	v_rcp_f32_e32 v165, v155
	v_mov_b32_e32 v150, s68
	v_mov_b32_e32 v151, s70
	v_mov_b32_e32 v152, s65
	v_mov_b32_e32 v153, s69
	global_store_dwordx4 v[170:171], v[146:149], off
	s_nop 1
	v_pk_add_f32 v[146:147], s[30:31], v[166:167]
	v_pk_add_f32 v[148:149], s[34:35], v[168:169]
	s_nop 0
	v_pk_add_f32 v[146:147], v[146:147], v[148:149]
	v_pk_add_f32 v[148:149], s[38:39], v[150:151]
	v_pk_add_f32 v[150:151], s[36:37], v[152:153]
	s_nop 0
	v_pk_add_f32 v[148:149], v[148:149], v[150:151]
	global_store_dwordx4 v[170:171], v[146:149], off offset:16
	s_nop 1
	v_fma_f32 v146, -v155, v165, 1.0
	v_fmac_f32_e32 v165, v146, v165
	v_div_scale_f32 v146, vcc, 1.0, v164, 1.0
	v_mul_f32_e32 v147, v146, v165
	v_fma_f32 v148, -v155, v147, v146
	v_fmac_f32_e32 v147, v148, v165
	v_fma_f32 v146, -v155, v147, v146
	v_div_fmas_f32 v146, v146, v165, v147
	v_div_fixup_f32 v148, v146, v164, 1.0
	v_lshl_add_u64 v[146:147], s[90:91], 0, v[156:157]
	global_store_dword v[146:147], v148, off
	s_branch .LBB0_28
.LBB0_31:
	s_or_b64 exec, exec, s[10:11]
	s_nop 0
	s_nop 0
	s_nop 0
	s_nop 0
	s_nop 0
	s_nop 0
	s_nop 0
	s_nop 0
	s_nop 0
	s_nop 0
	s_nop 0
	s_nop 0
	s_nop 0
	s_nop 0
	s_nop 0
